# c15: c13 + P0 transposes loop: spurious 32-step vmcnt ladder on the current item's registers dropped (one wait before the loop), so the next item's loads really overlap the LDS transpose
# baseline (speedup 1.0000x reference)
.LBB0_111:
	s_waitcnt vmcnt(0)
	s_mul_i32 s3, s37, 0x2100
	s_add_i32 s3, s3, 0
	s_add_u32 s6, s88, 0x12c00000
	v_lshrrev_b32_e32 v68, 3, v1
	v_lshlrev_b32_e32 v1, 3, v1
	s_addc_u32 s7, s89, 0
	v_and_b32_e32 v70, 56, v1
	s_add_u32 s8, s88, 0x13600000
	v_mul_u32_u24_e32 v1, 0x84, v70
	v_lshlrev_b32_e32 v5, 2, v68
	s_addc_u32 s9, s89, 0
	v_add3_u32 v1, s3, v1, v5
	v_cvt_f32_ubyte0_e32 v5, s48
	s_add_u32 s10, s88, 0x12e00000
	v_rcp_iflag_f32_e32 v5, v5
	s_addc_u32 s11, s89, 0
	s_add_u32 s12, s88, 0x12400000
	s_addc_u32 s13, s89, 0
	s_add_u32 s14, s88, 0x10400000
	v_mul_f32_e32 v5, 0x4f7ffffe, v5
	s_addc_u32 s15, s89, 0
	v_cvt_u32_f32_e32 v5, v5
	s_add_u32 s57, s88, 0xae00000
	s_addc_u32 s64, s89, 0
	s_add_u32 s65, s88, 0x200000
	s_addc_u32 s66, s89, 0
	v_lshl_add_u32 v3, v2, 2, s3
	s_sub_i32 s3, 0, s48
	v_readfirstlane_b32 s4, v5
	s_mul_i32 s3, s3, s4
	s_mov_b32 s5, 0
	s_mul_hi_u32 s3, s4, s3
	v_mov_b32_e32 v67, 0
	v_mul_u32_u24_e32 v4, 0x84, v71
	s_add_i32 s16, s4, s3
	s_mov_b32 s17, s5
	v_mov_b32_e32 v69, v67
	v_or_b32_e32 v72, 8, v68
	v_mov_b32_e32 v73, v67
	v_or_b32_e32 v74, 16, v68
	v_mov_b32_e32 v75, v67
	v_or_b32_e32 v76, 24, v68
	v_mov_b32_e32 v77, v67
	s_addk_i32 s33, 0x5601
	s_mov_b32 s67, 1
	v_lshlrev_b32_e32 v66, 2, v2
	v_add_u32_e32 v78, v3, v4
	v_mov_b32_e32 v79, 0xbfb8aa3b
	v_mov_b32_e32 v80, 0xbf317218
	s_mov_b64 s[18:19], s[16:17]
	s_branch .LBB0_114

.LBB0_148:
	s_lshl_b32 s29, s47, 6
	s_cmpk_gt_u32 s3, 0xab
	s_cselect_b64 vcc, -1, 0
	v_cndmask_b32_e32 v81, v79, v80, vcc
	v_cndmask_b32_e64 v81, 1.0, v81, s[20:21]
	v_mul_f32_e32 v34, v34, v81
	v_mul_f32_e32 v35, v35, v81
	ds_write2_b32 v78, v34, v35 offset1:66
	v_mul_f32_e32 v34, v36, v81
	v_mul_f32_e32 v35, v37, v81
	ds_write2_b32 v78, v34, v35 offset0:132 offset1:198
	v_mul_f32_e32 v34, v38, v81
	v_mul_f32_e32 v35, v39, v81
	v_add_u32_e32 v36, 0x400, v78
	ds_write2_b32 v36, v34, v35 offset0:8 offset1:74
	v_mul_f32_e32 v34, v40, v81
	v_mul_f32_e32 v35, v41, v81
	ds_write2_b32 v36, v34, v35 offset0:140 offset1:206
	v_mul_f32_e32 v34, v42, v81
	v_mul_f32_e32 v35, v43, v81
	v_add_u32_e32 v36, 0x800, v78
	ds_write2_b32 v36, v34, v35 offset0:16 offset1:82
	v_mul_f32_e32 v34, v44, v81
	v_mul_f32_e32 v35, v45, v81
	ds_write2_b32 v36, v34, v35 offset0:148 offset1:214
	v_mul_f32_e32 v34, v46, v81
	v_mul_f32_e32 v35, v47, v81
	v_add_u32_e32 v36, 0xc00, v78
	ds_write2_b32 v36, v34, v35 offset0:24 offset1:90
	v_mul_f32_e32 v34, v48, v81
	v_mul_f32_e32 v35, v49, v81
	ds_write2_b32 v36, v34, v35 offset0:156 offset1:222
	v_mul_f32_e32 v34, v50, v81
	v_mul_f32_e32 v35, v51, v81
	v_add_u32_e32 v36, 0x1000, v78
	ds_write2_b32 v36, v34, v35 offset0:32 offset1:98
	v_mul_f32_e32 v34, v52, v81
	v_mul_f32_e32 v35, v53, v81
	ds_write2_b32 v36, v34, v35 offset0:164 offset1:230
	v_mul_f32_e32 v34, v54, v81
	v_mul_f32_e32 v35, v55, v81
	v_add_u32_e32 v36, 0x1400, v78
	ds_write2_b32 v36, v34, v35 offset0:40 offset1:106
	v_mul_f32_e32 v34, v56, v81
	v_mul_f32_e32 v35, v57, v81
	ds_write2_b32 v36, v34, v35 offset0:172 offset1:238
	v_mul_f32_e32 v34, v58, v81
	v_mul_f32_e32 v35, v59, v81
	v_add_u32_e32 v36, 0x1800, v78
	ds_write2_b32 v36, v34, v35 offset0:48 offset1:114
	v_mul_f32_e32 v34, v60, v81
	v_mul_f32_e32 v35, v61, v81
	ds_write2_b32 v36, v34, v35 offset0:180 offset1:246
	v_mul_f32_e32 v34, v62, v81
	v_mul_f32_e32 v35, v63, v81
	v_add_u32_e32 v36, 0x1c00, v78
	ds_write2_b32 v36, v34, v35 offset0:56 offset1:122
	v_mul_f32_e32 v34, v64, v81
	v_mul_f32_e32 v35, v65, v81
	ds_write2_b32 v36, v34, v35 offset0:188 offset1:254
	s_waitcnt lgkmcnt(0)
	ds_read2_b32 v[34:35], v1 offset1:33
	ds_read2_b32 v[36:37], v1 offset0:66 offset1:99
	ds_read2_b32 v[40:41], v1 offset0:132 offset1:165
	ds_read2_b32 v[42:43], v1 offset0:198 offset1:231
	s_ashr_i32 s3, s29, 31
	v_mov_b32_e32 v39, s3
	v_or_b32_e32 v38, s29, v70
	s_ashr_i32 s29, s4, 31
	s_mov_b64 s[20:21], -1
	s_and_b64 vcc, exec, s[34:35]
	s_waitcnt lgkmcnt(3)
	v_cvt_pk_bf16_f32 v34, v34, v35
	s_waitcnt lgkmcnt(2)
	v_cvt_pk_bf16_f32 v35, v36, v37
	s_waitcnt lgkmcnt(1)
	v_cvt_pk_bf16_f32 v36, v40, v41
	s_waitcnt lgkmcnt(0)
	v_cvt_pk_bf16_f32 v37, v42, v43
	s_cbranch_vccz .LBB0_150
	v_add_u32_e32 v40, s4, v68
	v_mad_i64_i32 v[40:41], s[20:21], v40, s49, v[38:39]
	s_mov_b64 s[20:21], 0
